# P5 V-transpose staging: eight row loads issued together instead of one at a time
# baseline (speedup 1.0000x reference)
.LBB0_815:
	s_or_b64 exec, exec, s[88:89]
	s_waitcnt lgkmcnt(0)
	ds_read_b128 v[0:3], v122
	ds_read_b128 v[64:67], v122 offset:32
	ds_read_b128 v[4:7], v203
	ds_read_b128 v[218:221], v203 offset:32
	v_add_u32_e32 v68, v149, v150
	s_lshl_b32 s3, s14, 9
	s_add_u32 s88, s4, s3
	s_waitcnt lgkmcnt(1)
	v_mfma_f32_32x32x16_bf16 v[48:63], v[4:7], v[0:3], 0
	ds_read_b128 v[4:7], v203 offset:8704
	s_addc_u32 s89, s5, 0
	s_mov_b32 s3, 0
	s_waitcnt lgkmcnt(1)
	v_mfma_f32_32x32x16_bf16 v[48:63], v[218:221], v[64:67], v[48:63]
	s_waitcnt lgkmcnt(0)
	v_mfma_f32_32x32x16_bf16 v[32:47], v[4:7], v[0:3], 0
	ds_read_b128 v[4:7], v203 offset:17408
	s_waitcnt lgkmcnt(0)
	v_mfma_f32_32x32x16_bf16 v[16:31], v[4:7], v[0:3], 0
	ds_read_b128 v[4:7], v68
	ds_read_b128 v[222:225], v68 offset:32
	ds_read_b128 v[218:221], v203 offset:8736
	s_waitcnt lgkmcnt(0)
	v_mfma_f32_32x32x16_bf16 v[32:47], v[218:221], v[64:67], v[32:47]
	ds_read_b128 v[218:221], v203 offset:17440
	v_mfma_f32_32x32x16_bf16 v[0:15], v[4:7], v[0:3], 0
	s_waitcnt lgkmcnt(0)
	v_mfma_f32_32x32x16_bf16 v[16:31], v[218:221], v[64:67], v[16:31]
	v_mfma_f32_32x32x16_bf16 v[0:15], v[222:225], v[64:67], v[0:15]
	ds_read_b128 v[64:67], v122 offset:64
	ds_read_b128 v[218:221], v203 offset:64
	s_waitcnt lgkmcnt(0)
	v_mfma_f32_32x32x16_bf16 v[48:63], v[218:221], v[64:67], v[48:63]
	ds_read_b128 v[218:221], v203 offset:8768
	s_waitcnt lgkmcnt(0)
	v_mfma_f32_32x32x16_bf16 v[32:47], v[218:221], v[64:67], v[32:47]
	ds_read_b128 v[218:221], v203 offset:17472
	s_waitcnt lgkmcnt(0)
	v_mfma_f32_32x32x16_bf16 v[16:31], v[218:221], v[64:67], v[16:31]
	ds_read_b128 v[218:221], v68 offset:64
	s_waitcnt lgkmcnt(0)
	v_mfma_f32_32x32x16_bf16 v[0:15], v[218:221], v[64:67], v[0:15]
	ds_read_b128 v[64:67], v122 offset:96
	ds_read_b128 v[218:221], v203 offset:96
	s_waitcnt lgkmcnt(0)
	v_mfma_f32_32x32x16_bf16 v[48:63], v[218:221], v[64:67], v[48:63]
	ds_read_b128 v[218:221], v203 offset:8800
	s_waitcnt lgkmcnt(0)
	v_mfma_f32_32x32x16_bf16 v[32:47], v[218:221], v[64:67], v[32:47]
	ds_read_b128 v[218:221], v203 offset:17504
	s_waitcnt lgkmcnt(0)
	v_mfma_f32_32x32x16_bf16 v[16:31], v[218:221], v[64:67], v[16:31]
	ds_read_b128 v[218:221], v68 offset:96
	s_waitcnt lgkmcnt(0)
	v_mfma_f32_32x32x16_bf16 v[0:15], v[218:221], v[64:67], v[0:15]
	ds_read_b128 v[64:67], v122 offset:128
	ds_read_b128 v[218:221], v203 offset:128
	s_waitcnt lgkmcnt(0)
	v_mfma_f32_32x32x16_bf16 v[48:63], v[218:221], v[64:67], v[48:63]
	ds_read_b128 v[218:221], v203 offset:8832
	s_waitcnt lgkmcnt(0)
	v_mfma_f32_32x32x16_bf16 v[32:47], v[218:221], v[64:67], v[32:47]
	ds_read_b128 v[218:221], v203 offset:17536
	s_waitcnt lgkmcnt(0)
	v_mfma_f32_32x32x16_bf16 v[16:31], v[218:221], v[64:67], v[16:31]
	ds_read_b128 v[218:221], v68 offset:128
	s_waitcnt lgkmcnt(0)
	v_mfma_f32_32x32x16_bf16 v[0:15], v[218:221], v[64:67], v[0:15]
	ds_read_b128 v[64:67], v122 offset:160
	ds_read_b128 v[218:221], v203 offset:160
	s_waitcnt lgkmcnt(0)
	v_mfma_f32_32x32x16_bf16 v[48:63], v[218:221], v[64:67], v[48:63]
	ds_read_b128 v[218:221], v203 offset:8864
	s_waitcnt lgkmcnt(0)
	v_mfma_f32_32x32x16_bf16 v[32:47], v[218:221], v[64:67], v[32:47]
	ds_read_b128 v[218:221], v203 offset:17568
	s_waitcnt lgkmcnt(0)
	v_mfma_f32_32x32x16_bf16 v[16:31], v[218:221], v[64:67], v[16:31]
	ds_read_b128 v[218:221], v68 offset:160
	s_waitcnt lgkmcnt(0)
	v_mfma_f32_32x32x16_bf16 v[0:15], v[218:221], v[64:67], v[0:15]
	ds_read_b128 v[64:67], v122 offset:192
	ds_read_b128 v[218:221], v203 offset:192
	s_waitcnt lgkmcnt(0)
	v_mfma_f32_32x32x16_bf16 v[48:63], v[218:221], v[64:67], v[48:63]
	ds_read_b128 v[218:221], v203 offset:8896
	s_waitcnt lgkmcnt(0)
	v_mfma_f32_32x32x16_bf16 v[32:47], v[218:221], v[64:67], v[32:47]
	ds_read_b128 v[218:221], v203 offset:17600
	s_waitcnt lgkmcnt(0)
	v_mfma_f32_32x32x16_bf16 v[16:31], v[218:221], v[64:67], v[16:31]
	ds_read_b128 v[218:221], v68 offset:192
	s_waitcnt lgkmcnt(0)
	v_mfma_f32_32x32x16_bf16 v[0:15], v[218:221], v[64:67], v[0:15]
	ds_read_b128 v[64:67], v122 offset:224
	ds_read_b128 v[218:221], v203 offset:224
	s_waitcnt lgkmcnt(0)
	v_mfma_f32_32x32x16_bf16 v[48:63], v[218:221], v[64:67], v[48:63]
	ds_read_b128 v[218:221], v203 offset:8928
	s_waitcnt lgkmcnt(0)
	v_mfma_f32_32x32x16_bf16 v[32:47], v[218:221], v[64:67], v[32:47]
	ds_read_b128 v[218:221], v203 offset:17632
	s_waitcnt lgkmcnt(0)
	v_mfma_f32_32x32x16_bf16 v[16:31], v[218:221], v[64:67], v[16:31]
	ds_read_b128 v[218:221], v68 offset:224
	s_waitcnt lgkmcnt(0)
	v_mfma_f32_32x32x16_bf16 v[0:15], v[218:221], v[64:67], v[0:15]
	ds_read_b32 v64, v151
	s_waitcnt lgkmcnt(0)
	s_barrier
	v_mul_f32_e64 v62, v62, v64
	v_mul_f32_e64 v63, v63, v64
	v_pk_mul_f32 v[60:61], v[60:61], v[64:65] op_sel_hi:[1,0]
	v_pk_mul_f32 v[58:59], v[58:59], v[64:65] op_sel_hi:[1,0]
	v_pk_mul_f32 v[56:57], v[56:57], v[64:65] op_sel_hi:[1,0]
	v_pk_mul_f32 v[54:55], v[54:55], v[64:65] op_sel_hi:[1,0]
	v_pk_mul_f32 v[52:53], v[52:53], v[64:65] op_sel_hi:[1,0]
	v_pk_mul_f32 v[50:51], v[50:51], v[64:65] op_sel_hi:[1,0]
	v_pk_mul_f32 v[48:49], v[48:49], v[64:65] op_sel_hi:[1,0]
	v_pk_mul_f32 v[46:47], v[46:47], v[64:65] op_sel_hi:[1,0]
	v_pk_mul_f32 v[44:45], v[44:45], v[64:65] op_sel_hi:[1,0]
	v_pk_mul_f32 v[42:43], v[42:43], v[64:65] op_sel_hi:[1,0]
	v_pk_mul_f32 v[40:41], v[40:41], v[64:65] op_sel_hi:[1,0]
	v_pk_mul_f32 v[38:39], v[38:39], v[64:65] op_sel_hi:[1,0]
	v_pk_mul_f32 v[36:37], v[36:37], v[64:65] op_sel_hi:[1,0]
	v_pk_mul_f32 v[34:35], v[34:35], v[64:65] op_sel_hi:[1,0]
	v_pk_mul_f32 v[32:33], v[32:33], v[64:65] op_sel_hi:[1,0]
	v_pk_mul_f32 v[30:31], v[30:31], v[64:65] op_sel_hi:[1,0]
	v_pk_mul_f32 v[28:29], v[28:29], v[64:65] op_sel_hi:[1,0]
	v_pk_mul_f32 v[26:27], v[26:27], v[64:65] op_sel_hi:[1,0]
	v_pk_mul_f32 v[24:25], v[24:25], v[64:65] op_sel_hi:[1,0]
	v_pk_mul_f32 v[22:23], v[22:23], v[64:65] op_sel_hi:[1,0]
	v_pk_mul_f32 v[20:21], v[20:21], v[64:65] op_sel_hi:[1,0]
	v_pk_mul_f32 v[18:19], v[18:19], v[64:65] op_sel_hi:[1,0]
	v_pk_mul_f32 v[16:17], v[16:17], v[64:65] op_sel_hi:[1,0]
	v_pk_mul_f32 v[14:15], v[14:15], v[64:65] op_sel_hi:[1,0]
	v_pk_mul_f32 v[12:13], v[12:13], v[64:65] op_sel_hi:[1,0]
	v_pk_mul_f32 v[10:11], v[10:11], v[64:65] op_sel_hi:[1,0]
	v_pk_mul_f32 v[8:9], v[8:9], v[64:65] op_sel_hi:[1,0]
	v_pk_mul_f32 v[6:7], v[6:7], v[64:65] op_sel_hi:[1,0]
	v_pk_mul_f32 v[4:5], v[4:5], v[64:65] op_sel_hi:[1,0]
	v_pk_mul_f32 v[2:3], v[2:3], v[64:65] op_sel_hi:[1,0]
	v_pk_mul_f32 v[0:1], v[0:1], v[64:65] op_sel_hi:[1,0]
	v_or_b32_e32 v254, s97, v152
	v_ashrrev_i32_e32 v255, 31, v254
	v_lshlrev_b64 v[254:255], 12, v[254:255]
	v_lshl_add_u64 v[254:255], s[88:89], 0, v[254:255]
	v_lshl_add_u64 v[96:97], v[254:255], 0, v[92:93]
	v_or_b32_e32 v254, s97, v158
	v_ashrrev_i32_e32 v255, 31, v254
	v_lshlrev_b64 v[254:255], 12, v[254:255]
	v_lshl_add_u64 v[254:255], s[88:89], 0, v[254:255]
	v_lshl_add_u64 v[218:219], v[254:255], 0, v[92:93]
	v_or_b32_e32 v254, s97, v161
	v_ashrrev_i32_e32 v255, 31, v254
	v_lshlrev_b64 v[254:255], 12, v[254:255]
	v_lshl_add_u64 v[254:255], s[88:89], 0, v[254:255]
	v_lshl_add_u64 v[220:221], v[254:255], 0, v[92:93]
	v_or_b32_e32 v254, s97, v164
	v_ashrrev_i32_e32 v255, 31, v254
	v_lshlrev_b64 v[254:255], 12, v[254:255]
	v_lshl_add_u64 v[254:255], s[88:89], 0, v[254:255]
	v_lshl_add_u64 v[222:223], v[254:255], 0, v[92:93]
	global_load_dwordx4 v[64:67], v[96:97], off
	global_load_dwordx4 v[224:227], v[218:219], off
	global_load_dwordx4 v[228:231], v[220:221], off
	global_load_dwordx4 v[232:235], v[222:223], off
	global_load_dwordx4 v[236:239], v[96:97], off offset:32
	global_load_dwordx4 v[240:243], v[218:219], off offset:32
	global_load_dwordx4 v[244:247], v[220:221], off offset:32
	global_load_dwordx4 v[250:253], v[222:223], off offset:32
	s_waitcnt vmcnt(7)
	ds_write_b16 v153, v64
	ds_write_b16_d16_hi v154, v64 offset:272
	ds_write_b16 v153, v65 offset:544
	ds_write_b16_d16_hi v155, v65 offset:272
	ds_write_b16 v153, v66 offset:1088
	ds_write_b16_d16_hi v156, v66 offset:272
	ds_write_b16 v153, v67 offset:1632
	ds_write_b16_d16_hi v157, v67 offset:272
	s_waitcnt vmcnt(6)
	ds_write_b16 v159, v224
	ds_write_b16_d16_hi v154, v224 offset:336
	ds_write_b16 v160, v225 offset:544
	ds_write_b16_d16_hi v155, v225 offset:336
	ds_write_b16 v160, v226 offset:1088
	ds_write_b16_d16_hi v156, v226 offset:336
	ds_write_b16 v160, v227 offset:1632
	ds_write_b16_d16_hi v157, v227 offset:336
	s_waitcnt vmcnt(5)
	ds_write_b16 v162, v228
	ds_write_b16_d16_hi v154, v228 offset:400
	ds_write_b16 v163, v229 offset:544
	ds_write_b16_d16_hi v155, v229 offset:400
	ds_write_b16 v163, v230 offset:1088
	ds_write_b16_d16_hi v156, v230 offset:400
	ds_write_b16 v163, v231 offset:1632
	ds_write_b16_d16_hi v157, v231 offset:400
	s_waitcnt vmcnt(4)
	ds_write_b16 v165, v232
	ds_write_b16_d16_hi v154, v232 offset:464
	ds_write_b16 v166, v233 offset:544
	ds_write_b16_d16_hi v155, v233 offset:464
	ds_write_b16 v166, v234 offset:1088
	ds_write_b16_d16_hi v156, v234 offset:464
	ds_write_b16 v166, v235 offset:1632
	ds_write_b16_d16_hi v157, v235 offset:464
	s_waitcnt vmcnt(3)
	ds_write_b16 v167, v236
	ds_write_b16_d16_hi v168, v236 offset:272
	ds_write_b16 v153, v237 offset:4896
	ds_write_b16_d16_hi v169, v237 offset:272
	ds_write_b16 v153, v238 offset:5440
	ds_write_b16_d16_hi v170, v238 offset:272
	ds_write_b16 v153, v239 offset:5984
	ds_write_b16_d16_hi v171, v239 offset:272
	s_waitcnt vmcnt(2)
	ds_write_b16 v172, v240
	ds_write_b16_d16_hi v168, v240 offset:336
	ds_write_b16 v160, v241 offset:4896
	ds_write_b16_d16_hi v169, v241 offset:336
	ds_write_b16 v160, v242 offset:5440
	ds_write_b16_d16_hi v170, v242 offset:336
	ds_write_b16 v160, v243 offset:5984
	ds_write_b16_d16_hi v171, v243 offset:336
	s_waitcnt vmcnt(1)
	ds_write_b16 v173, v244
	ds_write_b16_d16_hi v168, v244 offset:400
	ds_write_b16 v163, v245 offset:4896
	ds_write_b16_d16_hi v169, v245 offset:400
	ds_write_b16 v163, v246 offset:5440
	ds_write_b16_d16_hi v170, v246 offset:400
	ds_write_b16 v163, v247 offset:5984
	ds_write_b16_d16_hi v171, v247 offset:400
	s_waitcnt vmcnt(0)
	ds_write_b16 v174, v250
	ds_write_b16_d16_hi v168, v250 offset:464
	ds_write_b16 v166, v251 offset:4896
	ds_write_b16_d16_hi v169, v251 offset:464
	ds_write_b16 v166, v252 offset:5440
	ds_write_b16_d16_hi v170, v252 offset:464
	ds_write_b16 v166, v253 offset:5984
	ds_write_b16_d16_hi v171, v253 offset:464
	s_waitcnt lgkmcnt(0)
	s_barrier
